# attention: workgroup-wide dynamic tile range after the diagonal block (rigorous bound, bit-identical) + prologue hoist
# speedup vs baseline: 1.0061x; 1.0061x over previous
.LBB0_297:
	s_cmpk_gt_i32 s46, 0x4f
	v_readlane_b32 s4, v245, 14
	s_cselect_b64 s[2:3], -1, 0
	s_cmp_lt_u32 s46, s4
	s_cselect_b64 s[4:5], -1, 0
	s_and_b64 s[2:3], s[2:3], s[4:5]
	s_andn2_b64 vcc, exec, s[2:3]
	s_mov_b64 s[2:3], -1
	s_cbranch_vccz .LBB0_352
	s_cmpk_gt_i32 s46, 0x4f
	v_readlane_b32 s2, v245, 13
	s_cselect_b32 s2, s2, 0
	s_sub_i32 s2, s46, s2
	s_bfe_u32 s4, s2, 0x30001
	s_and_b32 s3, s2, 1
	s_xor_b32 s5, s4, 7
	s_or_b32 s4, s4, 8
	s_cmp_eq_u32 s3, 0
	s_cselect_b32 s3, s4, s5
	s_mov_b64 s[4:5], s[0:1]
	s_mov_b64 s[12:13], s[0:1]
	s_load_dwordx2 s[4:5], s[4:5], 0x80
	s_load_dwordx2 s[74:75], s[12:13], 0x80
	s_mov_b64 s[12:13], s[0:1]
	s_ashr_i32 s2, s2, 4
	s_load_dwordx2 s[78:79], s[12:13], 0x28
	s_sub_i32 s12, 8, s2
	v_cvt_f32_i32_e32 v0, s12
	v_mov_b32_e32 v19, v220
	v_readlane_b32 s13, v245, 17
	v_exp_f32_e64 v0, -v0
	s_sub_i32 s55, 7, s2
	s_lshl_b32 s76, s55, 6
	v_ashrrev_i32_e32 v2, 5, v19
	v_readfirstlane_b32 s12, v0
	v_ashrrev_i32_e32 v0, 3, v19
	v_add_u32_e32 v0, s13, v0
	v_mul_lo_u32 v3, v0, s88
	v_lshrrev_b32_e32 v0, 1, v0
	s_add_i32 s13, s76, 0x200
	v_xor_b32_e32 v0, v0, v19
	v_add_u32_e32 v3, s13, v3
	v_lshlrev_b32_e32 v0, 3, v0
	v_readlane_b32 s13, v245, 16
	v_and_or_b32 v0, v0, 56, v3
	v_lshlrev_b32_e32 v4, 3, v19
	v_lshl_add_u32 v3, v2, 3, s13
	v_readlane_b32 s13, v245, 18
	s_add_i32 s13, s13, s76
	v_and_b32_e32 v20, 24, v4
	v_or_b32_e32 v9, s13, v20
	v_readlane_b32 s13, v245, 19
	s_waitcnt lgkmcnt(0)
	s_add_u32 s4, s4, s13
	s_addc_u32 s5, s5, 0
	s_add_u32 s60, s4, 0x13200000
	s_addc_u32 s61, s5, 0
	s_mul_i32 s4, s3, 0xc0000
	s_add_u32 s80, s60, s4
	v_lshlrev_b32_e32 v0, 1, v0
	s_addc_u32 s81, s61, 0
	s_movk_i32 s4, 0xfc00
	v_lshl_add_u64 v[4:5], s[80:81], 0, v[0:1]
	s_mov_b32 s5, -1
	v_lshl_add_u64 v[6:7], v[4:5], 0, s[4:5]
	v_readlane_b32 s5, v245, 22
	s_mov_b32 s4, m0
	s_mov_b32 m0, s5
	s_nop 0
	global_load_lds_dwordx4 v[6:7], off
	s_mov_b32 m0, s4
	s_mov_b64 s[4:5], 0x2fc00
	v_bfe_u32 v8, v19, 2, 3
	v_lshl_add_u64 v[6:7], v[4:5], 0, s[4:5]
	v_readlane_b32 s5, v245, 20
	s_mov_b32 s4, m0
	s_mov_b32 m0, s5
	s_nop 0
	global_load_lds_dwordx4 v[6:7], off
	s_mov_b32 m0, s4
	s_mov_b64 s[4:5], 0x5fc00
	v_or_b32_e32 v3, v3, v8
	v_lshl_add_u64 v[6:7], v[4:5], 0, s[4:5]
	v_readlane_b32 s5, v245, 21
	s_mov_b32 s4, m0
	s_mov_b32 m0, s5
	s_nop 0
	global_load_lds_dwordx4 v[6:7], off
	s_mov_b32 m0, s4
	s_mov_b64 s[4:5], 0x8fc00
	v_mul_lo_u32 v3, v3, s88
	v_lshl_add_u64 v[6:7], v[4:5], 0, s[4:5]
	v_readlane_b32 s5, v245, 23
	s_mov_b32 s4, m0
	s_mov_b32 m0, s5
	s_nop 0
	global_load_lds_dwordx4 v[6:7], off
	s_mov_b32 m0, s4
	v_add_lshl_u32 v170, v9, v3, 1
	s_mov_b32 s4, m0
	s_mov_b32 m0, s64
	s_nop 0
	global_load_lds_dwordx4 v[4:5], off
	s_mov_b32 m0, s4
	v_mov_b32_e32 v171, v1
	v_lshl_add_u64 v[4:5], s[80:81], 0, v[170:171]
	v_readlane_b32 s5, v245, 24
	s_mov_b32 s4, m0
	s_mov_b32 m0, s5
	s_nop 0
	global_load_lds_dwordx4 v[4:5], off
	s_mov_b32 m0, s4
	v_lshlrev_b32_e32 v4, 2, v19
	v_readlane_b32 s4, v245, 25
	v_and_b32_e32 v9, 4, v4
	v_bitop3_b32 v4, v4, v8, 4 bitop3:0x6c
	v_lshl_add_u32 v3, v19, 6, s4
	v_and_b32_e32 v3, 0xffffff80, v3
	v_add_u32_e32 v3, s63, v3
	v_lshl_add_u32 v4, v4, 4, v3
	s_ashr_i32 s101, s2, 31
	s_mov_b32 s100, s2
	s_lshl_b64 s[100:101], s[100:101], 2
	s_sub_u32 s100, s7, s100
	s_subb_u32 s101, s33, s101
	v_mov_b32_e32 v248, 0
	global_load_dword v249, v248, s[100:101] offset:28 sc1
	s_add_u32 s100, s80, 0x30000
	s_addc_u32 s101, s81, 0
	v_lshl_add_u64 v[250:251], s[100:101], 0, v[0:1]
	v_lshl_add_u64 v[252:253], s[100:101], 0, v[170:171]
	v_readlane_b32 s98, v245, 27
	s_mov_b32 s99, m0
	s_mov_b32 m0, s98
	s_nop 0
	global_load_lds_dwordx4 v[250:251], off
	v_readlane_b32 s98, v245, 28
	s_nop 0
	s_mov_b32 m0, s98
	s_nop 0
	global_load_lds_dwordx4 v[252:253], off
	s_add_u32 s100, s80, 0x60000
	s_addc_u32 s101, s81, 0
	v_lshl_add_u64 v[250:251], s[100:101], 0, v[0:1]
	v_lshl_add_u64 v[252:253], s[100:101], 0, v[170:171]
	v_readlane_b32 s98, v245, 29
	s_nop 0
	s_mov_b32 m0, s98
	s_nop 0
	global_load_lds_dwordx4 v[250:251], off
	v_readlane_b32 s98, v245, 30
	s_nop 0
	s_mov_b32 m0, s98
	s_nop 0
	global_load_lds_dwordx4 v[252:253], off
	s_mov_b32 m0, s99
	s_waitcnt vmcnt(5)
	s_barrier
	ds_read_b128 v[4:7], v4
	v_cmp_eq_u32_e32 vcc, 0, v19
	s_waitcnt lgkmcnt(0)
	v_lshlrev_b32_e32 v10, 16, v4
	v_and_b32_e32 v4, 0xffff0000, v4
	v_mul_f32_e32 v11, v4, v4
	v_fmac_f32_e32 v11, v10, v10
	v_lshlrev_b32_e32 v4, 16, v5
	v_fmac_f32_e32 v11, v4, v4
	v_and_b32_e32 v4, 0xffff0000, v5
	v_fmac_f32_e32 v11, v4, v4
	v_lshlrev_b32_e32 v4, 16, v6
	v_fmac_f32_e32 v11, v4, v4
	v_and_b32_e32 v4, 0xffff0000, v6
	v_fmac_f32_e32 v11, v4, v4
	v_lshlrev_b32_e32 v4, 16, v7
	v_fmac_f32_e32 v11, v4, v4
	v_and_b32_e32 v4, 0xffff0000, v7
	v_fmac_f32_e32 v11, v4, v4
	v_bitop3_b32 v4, v9, v8, 1 bitop3:0x36
	v_lshl_add_u32 v4, v4, 4, v3
	ds_read_b128 v[4:7], v4
	s_waitcnt lgkmcnt(0)
	v_lshlrev_b32_e32 v10, 16, v4
	v_fmac_f32_e32 v11, v10, v10
	v_and_b32_e32 v4, 0xffff0000, v4
	v_fmac_f32_e32 v11, v4, v4
	v_lshlrev_b32_e32 v4, 16, v5
	v_fmac_f32_e32 v11, v4, v4
	v_and_b32_e32 v4, 0xffff0000, v5
	v_fmac_f32_e32 v11, v4, v4
	v_lshlrev_b32_e32 v4, 16, v6
	v_fmac_f32_e32 v11, v4, v4
	v_and_b32_e32 v4, 0xffff0000, v6
	v_fmac_f32_e32 v11, v4, v4
	v_lshlrev_b32_e32 v4, 16, v7
	v_fmac_f32_e32 v11, v4, v4
	v_and_b32_e32 v4, 0xffff0000, v7
	v_fmac_f32_e32 v11, v4, v4
	v_bitop3_b32 v4, v9, v8, 2 bitop3:0x36
	v_lshl_add_u32 v4, v4, 4, v3
	ds_read_b128 v[4:7], v4
	s_waitcnt lgkmcnt(0)
	v_lshlrev_b32_e32 v10, 16, v4
	v_fmac_f32_e32 v11, v10, v10
	v_and_b32_e32 v4, 0xffff0000, v4
	v_fmac_f32_e32 v11, v4, v4
	v_lshlrev_b32_e32 v4, 16, v5
	v_fmac_f32_e32 v11, v4, v4
	v_and_b32_e32 v4, 0xffff0000, v5
	v_fmac_f32_e32 v11, v4, v4
	v_lshlrev_b32_e32 v4, 16, v6
	v_fmac_f32_e32 v11, v4, v4
	v_and_b32_e32 v4, 0xffff0000, v6
	v_fmac_f32_e32 v11, v4, v4
	v_lshlrev_b32_e32 v4, 16, v7
	v_fmac_f32_e32 v11, v4, v4
	v_and_b32_e32 v4, 0xffff0000, v7
	v_fmac_f32_e32 v11, v4, v4
	v_bitop3_b32 v4, v9, v8, 3 bitop3:0x36
	v_lshl_add_u32 v3, v4, 4, v3
	ds_read_b128 v[4:7], v3
	s_waitcnt lgkmcnt(0)
	v_lshlrev_b32_e32 v3, 16, v4
	v_fmac_f32_e32 v11, v3, v3
	v_and_b32_e32 v3, 0xffff0000, v4
	v_fmac_f32_e32 v11, v3, v3
	v_lshlrev_b32_e32 v3, 16, v5
	v_fmac_f32_e32 v11, v3, v3
	v_and_b32_e32 v3, 0xffff0000, v5
	v_fmac_f32_e32 v11, v3, v3
	v_lshlrev_b32_e32 v3, 16, v6
	v_fmac_f32_e32 v11, v3, v3
	v_and_b32_e32 v3, 0xffff0000, v6
	v_fmac_f32_e32 v11, v3, v3
	v_lshlrev_b32_e32 v3, 16, v7
	v_fmac_f32_e32 v11, v3, v3
	v_and_b32_e32 v3, 0xffff0000, v7
	v_fmac_f32_e32 v11, v3, v3
	ds_bpermute_b32 v3, v221, v11
	s_waitcnt lgkmcnt(0)
	v_max_f32_e32 v3, v3, v3
	v_max_f32_e32 v3, v11, v3
	ds_bpermute_b32 v4, v222, v3
	s_waitcnt lgkmcnt(0)
	v_max_f32_e32 v4, v4, v4
	v_max_f32_e32 v3, v3, v4
	ds_bpermute_b32 v4, v223, v3
	s_waitcnt lgkmcnt(0)
	v_max_f32_e32 v4, v4, v4
	v_max_f32_e32 v3, v3, v4
	ds_bpermute_b32 v4, v224, v3
	s_waitcnt lgkmcnt(0)
	v_max_f32_e32 v4, v4, v4
	v_max_f32_e32 v3, v3, v4
	ds_bpermute_b32 v4, v225, v3
	s_waitcnt lgkmcnt(0)
	v_max_f32_e32 v4, v4, v4
	v_max_f32_e32 v3, v3, v4
	ds_bpermute_b32 v4, v226, v3
	s_and_saveexec_b64 s[4:5], vcc
	s_cbranch_execz .LBB0_300
	s_waitcnt lgkmcnt(0)
	v_max_f32_e32 v4, v4, v4
	v_max_f32_e32 v3, v3, v3
	v_readlane_b32 s13, v245, 26
	v_max_f32_e32 v3, v3, v4
	s_nop 0
	v_mov_b32_e32 v4, s13
	ds_write_b32 v4, v3
	v_mov_b32_e32 v246, 0x18080
	v_mov_b32_e32 v247, 0
	ds_write_b32 v246, v247
.LBB0_300:
	s_or_b64 exec, exec, s[4:5]
	s_lshl_b32 s4, s3, 8
	v_readlane_b32 s5, v245, 15
	s_lshl_b32 s69, s3, 2
	s_ashr_i32 s3, s2, 31
	s_add_i32 s68, s4, s5
	s_lshl_b64 s[2:3], s[2:3], 2
	s_sub_u32 s2, s7, s2
	v_mov_b32_e32 v3, s11
	v_mov_b32_e32 v8, s89
	s_subb_u32 s3, s33, s3
	v_mov_b32_e32 v175, 0
	s_waitcnt lgkmcnt(0)
	s_barrier
	ds_read_b128 v[4:7], v3
	ds_read_b128 v[8:11], v8
	v_and_b32_e32 v185, 31, v19
	v_lshrrev_b32_e32 v3, 1, v19
	v_lshlrev_b32_e32 v172, 2, v2
	v_lshlrev_b32_e32 v12, 7, v185
	v_bitop3_b32 v2, v3, v2, 7 bitop3:0x6c
	v_mul_f32_e32 v18, s12, v235
	v_lshl_add_u32 v186, v2, 4, v12
	v_or_b32_e32 v2, s68, v185
	v_cvt_f32_i32_e32 v3, v172
	v_mul_f32_e32 v173, 0x42800000, v18
	s_mov_b32 s56, 0x41600000
	v_cvt_f32_u32_e32 v2, v2
	v_div_scale_f32 v58, s[2:3], v173, v173, s56
	v_cvt_f32_u32_e32 v13, s4
	v_rcp_f32_e32 v60, v58
	s_waitcnt lgkmcnt(1)
	v_max_f32_e32 v5, v5, v5
	v_max_f32_e32 v4, v4, v4
	v_sub_f32_e32 v187, v3, v2
	v_max_f32_e32 v2, v4, v5
	v_max3_f32 v2, v2, v6, v7
	v_fma_f32 v3, -v58, v60, 1.0
	v_add_f32_e32 v176, v187, v13
	s_waitcnt lgkmcnt(0)
	v_max3_f32 v23, v2, v8, v9
	v_fmac_f32_e32 v60, v3, v60
	v_pk_add_f32 v[2:3], v[176:177], s[14:15] op_sel_hi:[0,1]
	v_max3_f32 v23, v23, v10, v11
	v_and_b32_e32 v24, 0x7fffffff, v2
	s_mov_b32 s2, 0xf800000
	v_and_b32_e32 v25, 0x7fffffff, v3
	v_pk_add_f32 v[12:13], v[176:177], s[22:23] op_sel_hi:[0,1]
	v_pk_add_f32 v[14:15], v[176:177], s[24:25] op_sel_hi:[0,1]
	v_pk_add_f32 v[16:17], v[176:177], s[26:27] op_sel_hi:[0,1]
	v_add_f32_e32 v26, 1.0, v176
	v_and_b32_e32 v11, 0x7fffffff, v13
	v_and_b32_e32 v10, 0x7fffffff, v12
	v_and_b32_e32 v13, 0x7fffffff, v15
	v_and_b32_e32 v12, 0x7fffffff, v14
	v_and_b32_e32 v15, 0x7fffffff, v17
	v_and_b32_e32 v14, 0x7fffffff, v16
	v_and_b32_e32 v22, 0x7fffffff, v176
	v_pk_mul_f32 v[16:17], v[14:15], v[18:19] op_sel_hi:[1,0] neg_lo:[0,1] neg_hi:[0,1]
	v_pk_add_f32 v[8:9], v[176:177], s[20:21] op_sel_hi:[0,1]
	v_and_b32_e32 v9, 0x7fffffff, v9
	v_and_b32_e32 v8, 0x7fffffff, v8
	v_readlane_b32 s55, v245, 28
	v_pk_add_f32 v[4:5], v[176:177], s[16:17] op_sel_hi:[0,1]
	v_pk_add_f32 v[6:7], v[176:177], s[18:19] op_sel_hi:[0,1]
	v_xor_b32_e32 v188, 32, v186
	v_and_b32_e32 v5, 0x7fffffff, v5
	v_and_b32_e32 v4, 0x7fffffff, v4
	v_and_b32_e32 v7, 0x7fffffff, v7
	v_and_b32_e32 v6, 0x7fffffff, v6
	v_add_u32_e32 v61, 0, v188
	v_add_u32_e32 v189, s52, v186
	v_add_u32_e32 v192, s52, v188
	v_div_scale_f32 v59, s[4:5], s56, v173, s56
	v_pk_add_f32 v[42:43], v[176:177], s[28:29] op_sel_hi:[0,1]
	v_pk_add_f32 v[44:45], v[176:177], s[30:31] op_sel_hi:[0,1]
	v_pk_add_f32 v[46:47], v[176:177], s[34:35] op_sel_hi:[0,1]
	v_pk_add_f32 v[48:49], v[176:177], s[36:37] op_sel_hi:[0,1]
	v_pk_add_f32 v[50:51], v[176:177], s[38:39] op_sel_hi:[0,1]
	v_pk_add_f32 v[52:53], v[176:177], s[40:41] op_sel_hi:[0,1]
	v_pk_add_f32 v[54:55], v[176:177], s[42:43] op_sel_hi:[0,1]
	v_pk_add_f32 v[56:57], v[176:177], s[44:45] op_sel_hi:[0,1]
	v_and_b32_e32 v57, 0x7fffffff, v57
	v_and_b32_e32 v56, 0x7fffffff, v56
	v_and_b32_e32 v55, 0x7fffffff, v55
	v_and_b32_e32 v54, 0x7fffffff, v54
	v_and_b32_e32 v53, 0x7fffffff, v53
	v_and_b32_e32 v52, 0x7fffffff, v52
	v_and_b32_e32 v51, 0x7fffffff, v51
	v_and_b32_e32 v50, 0x7fffffff, v50
	v_and_b32_e32 v49, 0x7fffffff, v49
	v_and_b32_e32 v48, 0x7fffffff, v48
	v_and_b32_e32 v47, 0x7fffffff, v47
	v_and_b32_e32 v46, 0x7fffffff, v46
	v_and_b32_e32 v45, 0x7fffffff, v45
	s_waitcnt vmcnt(4)
	v_mul_f32_e32 v2, v23, v249
	v_mul_f32_e32 v3, 0x4f800000, v2
	v_cmp_gt_f32_e32 vcc, s2, v2
	v_and_b32_e32 v23, 0x7fffffff, v26
	v_and_b32_e32 v44, 0x7fffffff, v44
	v_cndmask_b32_e32 v21, v2, v3, vcc
	v_sqrt_f32_e32 v27, v21
	v_pk_mul_f32 v[2:3], v[22:23], v[18:19] op_sel_hi:[1,0] neg_lo:[0,1] neg_hi:[0,1]
	v_and_b32_e32 v43, 0x7fffffff, v43
	v_and_b32_e32 v42, 0x7fffffff, v42
	v_add_u32_e32 v14, -1, v27
	v_add_u32_e32 v15, 1, v27
	v_fma_f32 v22, -v14, v27, v21
	v_fma_f32 v23, -v15, v27, v21
	v_cmp_ge_f32_e64 s[2:3], 0, v22
	v_pk_mul_f32 v[96:97], v[42:43], v[18:19] op_sel_hi:[1,0] neg_lo:[0,1] neg_hi:[0,1]
	v_pk_mul_f32 v[94:95], v[44:45], v[18:19] op_sel_hi:[1,0] neg_lo:[0,1] neg_hi:[0,1]
	v_cndmask_b32_e64 v14, v27, v14, s[2:3]
	v_cmp_lt_f32_e64 s[2:3], 0, v23
	v_pk_mul_f32 v[92:93], v[46:47], v[18:19] op_sel_hi:[1,0] neg_lo:[0,1] neg_hi:[0,1]
	v_pk_mul_f32 v[90:91], v[48:49], v[18:19] op_sel_hi:[1,0] neg_lo:[0,1] neg_hi:[0,1]
	v_cndmask_b32_e64 v14, v14, v15, s[2:3]
	v_mul_f32_e32 v15, 0x37800000, v14
	v_cndmask_b32_e32 v14, v14, v15, vcc
	v_cmp_class_f32_e32 vcc, v21, v232
	v_pk_mul_f32 v[88:89], v[50:51], v[18:19] op_sel_hi:[1,0] neg_lo:[0,1] neg_hi:[0,1]
	v_pk_mul_f32 v[86:87], v[52:53], v[18:19] op_sel_hi:[1,0] neg_lo:[0,1] neg_hi:[0,1]
	v_cndmask_b32_e32 v14, v14, v21, vcc
	v_mul_f32_e32 v21, 0x3f828f5c, v14
	v_add_f32_e32 v246, 0x42000000, v21
	s_nop 0
	v_readfirstlane_b32 s98, v246
	v_fmaak_f32 v22, 2.0, v21, 0x42000000
	v_div_scale_f32 v23, s[2:3], v18, v18, v22
	v_rcp_f32_e32 v26, v23
	v_pk_mul_f32 v[14:15], v[12:13], v[18:19] op_sel_hi:[1,0] neg_lo:[0,1] neg_hi:[0,1]
	v_div_scale_f32 v12, vcc, v22, v18, v22
	v_fma_f32 v13, -v23, v26, 1.0
	v_fmac_f32_e32 v26, v13, v26
	v_mul_f32_e32 v13, v12, v26
	v_fma_f32 v27, -v23, v13, v12
	v_fmac_f32_e32 v13, v27, v26
	v_fma_f32 v12, -v23, v13, v12
	v_div_fmas_f32 v12, v12, v26, v13
	v_div_fixup_f32 v22, v12, v18, v22
	v_cvt_i32_f32_e32 v23, v22
	v_cmp_gt_f32_e32 vcc, s90, v22
	v_pk_mul_f32 v[12:13], v[10:11], v[18:19] op_sel_hi:[1,0] neg_lo:[0,1] neg_hi:[0,1]
	v_pk_mul_f32 v[10:11], v[8:9], v[18:19] op_sel_hi:[1,0] neg_lo:[0,1] neg_hi:[0,1]
	v_readfirstlane_b32 s2, v23
	s_add_i32 s12, s2, 1
	s_and_b64 s[2:3], vcc, exec
	s_cselect_b32 s2, s12, 0x2000
	s_add_i32 s12, s2, 62
	s_add_i32 s2, s2, -2
	s_ashr_i32 s12, s12, 6
	s_ashr_i32 s2, s2, 6
	s_xor_b32 s3, s69, 60
	s_min_i32 s77, s69, s12
	s_add_i32 s2, s2, 1
	s_min_i32 s2, s3, s2
	s_add_i32 s82, s77, 4
	s_add_u32 s12, s80, 0x30000
	s_addc_u32 s13, s81, 0
	s_add_u32 s12, s80, 0x60000
	v_readlane_b32 s13, v245, 27
	s_addc_u32 s13, s81, 0
	v_add_u32_e32 v26, 0, v186
	v_readlane_b32 s12, v245, 29
	v_readlane_b32 s12, v245, 30
	v_pk_mul_f32 v[8:9], v[6:7], v[18:19] op_sel_hi:[1,0] neg_lo:[0,1] neg_hi:[0,1]
	v_pk_mul_f32 v[6:7], v[4:5], v[18:19] op_sel_hi:[1,0] neg_lo:[0,1] neg_hi:[0,1]
	v_pk_mul_f32 v[4:5], v[24:25], v[18:19] op_sel_hi:[1,0] neg_lo:[0,1] neg_hi:[0,1]
	ds_read_b128 v[22:25], v26
	ds_read_b128 v[26:29], v26 offset:4096
	ds_read_b128 v[30:33], v61
	ds_read_b128 v[34:37], v189
	ds_read_b128 v[38:41], v192
	s_waitcnt lgkmcnt(1)
	v_mfma_f32_32x32x16_bf16 v[98:113], v[22:25], v[34:37], v[2:17]
	v_mul_f32_e32 v22, v59, v60
	v_fma_f32 v23, -v58, v22, v59
	v_fmac_f32_e32 v22, v23, v60
	v_mul_f32_e64 v84, v54, -v18
	v_mul_f32_e64 v85, v55, -v18
	v_pk_mul_f32 v[82:83], v[56:57], v[18:19] op_sel_hi:[1,0] neg_lo:[0,1] neg_hi:[0,1]
	v_fma_f32 v23, -v58, v22, v59
	s_mov_b64 vcc, s[4:5]
	v_mfma_f32_32x32x16_bf16 v[82:97], v[26:29], v[34:37], v[82:97]
	v_div_fmas_f32 v26, v23, v60, v22
	ds_read_b128 v[22:25], v61 offset:4096
	v_div_fixup_f32 v26, v26, v173, s56
	v_cmp_gt_f32_e32 vcc, s24, v21
	s_add_i32 s83, s82, s2
	s_cmp_lt_i32 s83, 1
	v_cndmask_b32_e32 v21, 0, v26, vcc
	s_waitcnt lgkmcnt(1)
	v_mfma_f32_32x32x16_bf16 v[98:113], v[30:33], v[38:41], v[98:113]
	v_min_f32_e32 v21, 0x42800000, v21
	s_nop 0
	v_readfirstlane_b32 s3, v21
	s_waitcnt lgkmcnt(0)
	v_mfma_f32_32x32x16_bf16 v[82:97], v[22:25], v[38:41], v[82:97]
	s_cbranch_scc1 .LBB0_350
	v_lshrrev_b32_e32 v21, 2, v19
	v_lshlrev_b32_e32 v19, 1, v19
	v_cvt_i32_f32_e32 v193, s3
	v_and_or_b32 v21, v21, 3, v172
	v_and_or_b32 v19, v19, 32, v20
	v_lshl_or_b32 v19, v21, 6, v19
	v_mov_b32_e32 v50, v1
	v_mov_b32_e32 v51, v1
	v_mov_b32_e32 v64, v1
	v_mov_b32_e32 v65, v1
	v_xor_b32_e32 v178, 0x80000000, v18
	v_add_u32_e32 v195, 0x2000, v19
	v_mul_f32_e32 v196, 0x42000000, v18
	v_mul_f32_e32 v197, 0xc2000000, v18
	s_add_i32 s86, s2, s77
	v_mov_b32_e32 v52, v1
	v_mov_b32_e32 v53, v1
	v_mov_b32_e32 v54, v1
	v_mov_b32_e32 v55, v1
	v_mov_b32_e32 v56, v1
	v_mov_b32_e32 v57, v1
	v_mov_b32_e32 v58, v1
	v_mov_b32_e32 v59, v1
	v_mov_b32_e32 v60, v1
	v_mov_b32_e32 v61, v1
	v_mov_b32_e32 v62, v1
	v_mov_b32_e32 v63, v1
	v_mov_b64_e32 v[18:19], v[50:51]
	v_mov_b64_e32 v[80:81], v[64:65]
	v_mov_b64_e32 v[34:35], v[50:51]
	v_mov_b32_e32 v180, v178
	v_mov_b32_e32 v181, v178
	v_xor_b32_e32 v194, 64, v186
	s_sub_i32 s84, s69, s77
	s_or_b32 s85, s69, 3
	v_xor_b32_e32 v198, 0x60, v186
	s_add_i32 s86, s86, 4
	s_add_i32 s87, s77, 3
	s_mov_b32 s88, 0
	v_mov_b32_e32 v174, v1
	v_mov_b32_e32 v175, v1
	v_mov_b32_e32 v182, 0
	s_mov_b32 s89, s69
	v_mov_b64_e32 v[20:21], v[52:53]
	v_mov_b64_e32 v[22:23], v[54:55]
	v_mov_b64_e32 v[24:25], v[56:57]
	v_mov_b64_e32 v[26:27], v[58:59]
	v_mov_b64_e32 v[28:29], v[60:61]
	v_mov_b64_e32 v[30:31], v[62:63]
	v_mov_b64_e32 v[32:33], v[64:65]
	v_mov_b64_e32 v[78:79], v[62:63]
	v_mov_b64_e32 v[76:77], v[60:61]
	v_mov_b64_e32 v[74:75], v[58:59]
	v_mov_b64_e32 v[72:73], v[56:57]
	v_mov_b64_e32 v[70:71], v[54:55]
	v_mov_b64_e32 v[68:69], v[52:53]
	v_mov_b64_e32 v[66:67], v[50:51]
	v_mov_b64_e32 v[36:37], v[52:53]
	v_mov_b64_e32 v[38:39], v[54:55]
	v_mov_b64_e32 v[40:41], v[56:57]
	v_mov_b64_e32 v[42:43], v[58:59]
	v_mov_b64_e32 v[44:45], v[60:61]
	v_mov_b64_e32 v[46:47], v[62:63]
	v_mov_b64_e32 v[48:49], v[64:65]
	s_mov_b32 s90, 0
	s_add_i32 s2, s90, 2
	s_cmp_ge_i32 s2, s83
	s_mov_b64 s[2:3], -1
	s_cbranch_scc0 .LBB0_303

.LBB0_305:
	s_add_i32 s3, s90, 3
	s_barrier
	s_cmp_eq_u32 s90, 4
	s_cbranch_scc1 .Ldyn_update
.Ldyn_back:
	s_cmp_ge_i32 s3, s83
	s_cbranch_scc1 .LBB0_310
	s_cmp_eq_u32 s90, 0
	s_mov_b32 s2, s85
	s_cbranch_scc1 .LBB0_309
	s_cmp_lt_i32 s3, s82
	s_mov_b32 s2, s89
	s_cbranch_scc1 .LBB0_309
	s_add_i32 s2, s3, s84

.LBB0_346:
	s_cmp_eq_u32 s12, 4
	s_cbranch_scc1 .Ldyn_post

.Ldyn_post:
	v_min_f32_e32 v246, v174, v175
	v_log_f32_e32 v246, v246
	v_sub_f32_e32 v247, s98, v182
	s_nop 0
	v_sub_f32_e32 v246, v247, v246
	v_max_f32_e32 v246, 0, v246
	v_mov_b32_e32 v247, 0x18080
	ds_max_u32 v247, v246
	s_waitcnt lgkmcnt(0)
	s_branch .Ldyn_post_back
.Ldyn_update:
	v_mov_b32_e32 v246, 0x18080
	ds_read_b32 v246, v246
	v_rcp_f32_e32 v247, v173
	s_waitcnt lgkmcnt(0)
	v_mul_f32_e32 v246, v246, v247
	v_mul_f32_e32 v246, 0x42800800, v246
	v_min_f32_e32 v246, 0x46000000, v246
	v_cvt_i32_f32_e32 v246, v246
	s_nop 0
	v_readfirstlane_b32 s99, v246
	s_add_i32 s99, s99, 2
	s_add_i32 s100, s99, 62
	s_ashr_i32 s100, s100, 6
	s_add_i32 s101, s99, -2
	s_ashr_i32 s101, s101, 6
	s_add_i32 s101, s101, 1
	v_readfirstlane_b32 s99, v193
	s_max_i32 s100, s100, s99
	s_max_i32 s101, s101, s99
	s_max_i32 s100, s100, 3
	s_max_i32 s101, s101, 3
	s_sub_i32 s99, s83, s82
	s_min_i32 s100, s100, s77
	s_min_i32 s101, s101, s99
	s_mov_b32 s77, s100
	s_add_i32 s82, s77, 4
	s_add_i32 s83, s82, s101
	s_mov_b32 s86, s83
	s_sub_i32 s84, s69, s77
	s_add_i32 s87, s77, 3
	s_branch .Ldyn_back
